# SWA prompt unit (phase 13) V^T staging: same lane remap (4 adjacent lanes read 64 contiguous bytes of a row)
# speedup vs baseline: 1.0281x; 1.0031x over previous
.LBB0_78:
	s_and_b64 vcc, exec, s[4:5]
	s_cbranch_vccz .LBB0_133
	s_cmp_eq_u32 s72, 13
	s_cbranch_scc0 .LBB0_133
	v_and_b32_e32 v26, 3, v191
	v_lshrrev_b32_e32 v27, 2, v191
	v_lshl_or_b32 v26, v26, 7, v27
	v_add_u32_e32 v27, 0x200, v26
	v_readlane_b32 s0, v254, 59
	s_lshl_b32 s4, s0, 11
	s_ashr_i32 s5, s4, 31
	s_lshl_b64 s[4:5], s[4:5], 2
	s_add_u32 s4, s38, s4
	s_addc_u32 s5, s39, s5
	v_add_u32_e32 v4, 0x200, v191
	s_cmp_lg_u32 s0, 0
	v_readlane_b32 s0, v252, 11
	v_ashrrev_i32_e32 v1, 31, v191
	v_ashrrev_i32_e32 v5, 31, v4
	s_cselect_b32 s0, s0, 0
	v_lshrrev_b32_e32 v2, 29, v1
	v_lshrrev_b32_e32 v6, 29, v5
	v_lshrrev_b32_e32 v1, 25, v1
	v_lshrrev_b32_e32 v5, 25, v5
	v_writelane_b32 v255, s4, 0
	s_cmp_lg_u32 s0, 2
	v_add_u32_e32 v6, v4, v6
	v_add_u32_e32 v8, 0x400, v191
	v_add_u32_e32 v10, 0x600, v191
	v_add_u32_e32 v1, v26, v1
	v_add_u32_e32 v5, v27, v5
	v_writelane_b32 v255, s5, 1
	s_cselect_b64 s[4:5], -1, 0
	v_readlane_b32 s15, v254, 58
	v_ashrrev_i32_e32 v71, 3, v6
	v_and_b32_e32 v6, -8, v6
	v_ashrrev_i32_e32 v9, 31, v8
	v_ashrrev_i32_e32 v11, 31, v10
	v_ashrrev_i32_e32 v12, 7, v1
	v_and_b32_e32 v1, 0xffffff80, v1
	s_waitcnt lgkmcnt(0)
	v_ashrrev_i32_e32 v13, 7, v5
	v_and_b32_e32 v5, 0xffffff80, v5
	v_writelane_b32 v255, s4, 2
	s_cmp_lg_u32 s0, 1
	s_mul_i32 s0, s15, 0x2100
	v_sub_u32_e32 v6, v4, v6
	v_lshrrev_b32_e32 v9, 29, v9
	v_lshrrev_b32_e32 v11, 29, v11
	v_sub_u32_e32 v1, v26, v1
	v_sub_u32_e32 v4, v27, v5
	v_writelane_b32 v255, s5, 3
	s_cselect_b64 s[4:5], -1, 0
	s_add_i32 s0, s0, 0
	v_add_u32_e32 v2, v191, v2
	v_add_u32_e32 v9, v8, v9
	v_add_u32_e32 v11, v10, v11
	v_lshlrev_b32_e32 v74, 1, v1
	v_lshlrev_b32_e32 v76, 1, v4
	v_writelane_b32 v255, s4, 4
	s_add_i32 s0, s0, 0x11400
	v_ashrrev_i32_e32 v70, 3, v2
	s_movk_i32 s6, 0xc00
	v_ashrrev_i32_e32 v72, 3, v9
	v_ashrrev_i32_e32 v73, 3, v11
	v_or_b32_e32 v75, 1, v74
	v_or_b32_e32 v77, 1, v76
	v_writelane_b32 v255, s5, 5
	v_mad_u64_u32 v[36:37], s[4:5], v70, s6, 0
	v_mad_u64_u32 v[40:41], s[4:5], v71, s6, 0
	v_mad_u64_u32 v[44:45], s[4:5], v72, s6, 0
	v_mad_u64_u32 v[48:49], s[4:5], v73, s6, 0
	v_mad_u64_u32 v[52:53], s[4:5], v74, s6, 0
	v_mad_u64_u32 v[56:57], s[4:5], v75, s6, 0
	v_mad_u64_u32 v[58:59], s[4:5], v76, s6, 0
	v_mad_u64_u32 v[62:63], s[4:5], v77, s6, 0
	s_cmp_lt_i32 s15, 32
	s_cselect_b64 s[4:5], -1, 0
	v_writelane_b32 v255, s4, 6
	v_and_b32_e32 v65, 15, v191
	s_movk_i32 s7, 0x1080
	v_writelane_b32 v255, s5, 7
	s_max_i32 s4, s15, 1
	s_add_i32 s5, s4, -1
	v_mov_b32_e32 v14, s0
	s_movk_i32 s0, 0x210
	s_lshl_b32 s4, s4, 4
	v_lshlrev_b32_e32 v54, 3, v12
	v_mul_lo_u32 v12, v12, s7
	v_mul_lo_u32 v5, v13, s7
	v_mad_u32_u24 v79, v65, s0, v14
	s_lshl_b32 s0, s5, 5
	s_lshl_b32 s5, s5, 4
	s_add_i32 s6, s4, 16
	s_add_i32 s7, s4, 32
	s_add_i32 s8, s4, 48
	s_add_i32 s9, s4, 64
	s_add_i32 s10, s4, 0x50
	s_add_i32 s11, s4, 0x60
	s_add_i32 s12, s4, 0x70
	s_add_i32 s13, s4, 0x80
	v_lshrrev_b32_e32 v0, 4, v192
	v_and_b32_e32 v2, -8, v2
	s_movk_i32 s14, 0x90
	v_and_b32_e32 v9, -8, v9
	v_and_b32_e32 v11, -8, v11
	v_or_b32_e32 v14, s5, v65
	v_or_b32_e32 v15, s4, v65
	v_or_b32_e32 v16, s6, v65
	v_or_b32_e32 v17, s7, v65
	v_or_b32_e32 v18, s8, v65
	v_or_b32_e32 v19, s9, v65
	v_or_b32_e32 v20, s10, v65
	v_or_b32_e32 v21, s11, v65
	v_or_b32_e32 v22, s12, v65
	v_or_b32_e32 v23, s13, v65
	v_sub_u32_e32 v2, v191, v2
	v_mul_lo_u32 v3, v70, s14
	v_mul_lo_u32 v7, v71, s14
	v_sub_u32_e32 v8, v8, v9
	v_mul_lo_u32 v9, v72, s14
	v_sub_u32_e32 v10, v10, v11
	v_mul_lo_u32 v11, v73, s14
	v_lshlrev_b32_e32 v64, 3, v0
	v_and_b32_e32 v78, 48, v191
	v_lshlrev_b32_e32 v0, 2, v0
	s_add_i32 s0, s0, 0
	v_mul_lo_u32 v14, v14, s14
	v_mul_lo_u32 v15, v15, s14
	v_mul_lo_u32 v16, v16, s14
	v_mul_lo_u32 v17, v17, s14
	v_mul_lo_u32 v18, v18, s14
	v_mul_lo_u32 v19, v19, s14
	v_mul_lo_u32 v20, v20, s14
	v_mul_lo_u32 v21, v21, s14
	v_mul_lo_u32 v22, v22, s14
	v_mul_lo_u32 v23, v23, s14
	v_or_b32_e32 v25, 48, v192
	v_lshlrev_b32_e32 v38, 3, v2
	v_add_u32_e32 v3, 0, v3
	v_lshlrev_b32_e32 v2, 4, v2
	v_lshlrev_b32_e32 v42, 3, v6
	v_add_u32_e32 v7, 0, v7
	v_lshlrev_b32_e32 v6, 4, v6
	v_lshlrev_b32_e32 v46, 3, v8
	v_add_u32_e32 v9, 0, v9
	v_lshlrev_b32_e32 v8, 4, v8
	v_lshlrev_b32_e32 v50, 3, v10
	v_add_u32_e32 v11, 0, v11
	v_lshlrev_b32_e32 v10, 4, v10
	v_add_u32_e32 v12, 0, v12
	v_lshlrev_b32_e32 v1, 2, v1
	v_lshlrev_b32_e32 v60, 3, v13
	v_add_u32_e32 v5, 0, v5
	v_lshlrev_b32_e32 v4, 2, v4
	v_mul_u32_u24_e32 v13, 0x210, v65
	v_add_u32_e32 v14, 0, v14
	v_add_u32_e32 v15, 0, v15
	v_add_u32_e32 v16, 0, v16
	v_add_u32_e32 v17, 0, v17
	v_add_u32_e32 v18, 0, v18
	v_add_u32_e32 v19, 0, v19
	v_add_u32_e32 v20, 0, v20
	v_add_u32_e32 v21, 0, v21
	v_add_u32_e32 v22, 0, v22
	v_add_u32_e32 v23, 0, v23
	v_or_b32_e32 v80, s5, v0
	v_or_b32_e32 v84, s4, v0
	v_or_b32_e32 v88, s6, v0
	v_or_b32_e32 v92, s7, v0
	v_or_b32_e32 v96, s8, v0
	v_or_b32_e32 v100, s9, v0
	v_or_b32_e32 v104, s10, v0
	v_or_b32_e32 v108, s11, v0
	v_add_u32_e32 v24, s0, v78
	v_mul_u32_u24_e32 v25, 0x210, v25
	s_lshl_b32 s0, s15, 4
	v_ashrrev_i32_e32 v39, 31, v38
	v_ashrrev_i32_e32 v43, 31, v42
	v_ashrrev_i32_e32 v47, 31, v46
	v_ashrrev_i32_e32 v51, 31, v50
	v_ashrrev_i32_e32 v55, 31, v54
	v_ashrrev_i32_e32 v61, 31, v60
	v_or_b32_e32 v81, 1, v80
	v_or_b32_e32 v82, 2, v80
	v_or_b32_e32 v83, 3, v80
	v_or_b32_e32 v85, 1, v84
	v_or_b32_e32 v86, 2, v84
	v_or_b32_e32 v87, 3, v84
	v_or_b32_e32 v89, 1, v88
	v_or_b32_e32 v90, 2, v88
	v_or_b32_e32 v91, 3, v88
	v_or_b32_e32 v93, 1, v92
	v_or_b32_e32 v94, 2, v92
	v_or_b32_e32 v95, 3, v92
	v_or_b32_e32 v97, 1, v96
	v_or_b32_e32 v98, 2, v96
	v_or_b32_e32 v99, 3, v96
	v_or_b32_e32 v101, 1, v100
	v_or_b32_e32 v102, 2, v100
	v_or_b32_e32 v103, 3, v100
	v_or_b32_e32 v105, 1, v104
	v_or_b32_e32 v106, 2, v104
	v_or_b32_e32 v107, 3, v104
	v_or_b32_e32 v109, 1, v108
	v_or_b32_e32 v110, 2, v108
	v_or_b32_e32 v111, 3, v108
	v_or_b32_e32 v112, s12, v0
	v_or_b32_e32 v113, s13, v0
	v_writelane_b32 v255, s0, 8
	v_add_u32_e32 v114, v3, v2
	v_add_u32_e32 v115, v7, v6
	v_add_u32_e32 v116, v9, v8
	v_add_u32_e32 v117, v11, v10
	v_add_u32_e32 v118, v12, v1
	v_add_u32_e32 v119, v5, v4
	v_add_u32_e32 v120, v14, v78
	v_add_u32_e32 v121, v15, v78
	v_add_u32_e32 v122, v16, v78
	v_add_u32_e32 v123, v17, v78
	v_add_u32_e32 v124, v18, v78
	v_add_u32_e32 v125, v19, v78
	v_add_u32_e32 v126, v20, v78
	v_add_u32_e32 v127, v21, v78
	v_add_u32_e32 v128, v22, v78
	v_add_u32_e32 v129, v23, v78
	v_add_u32_e32 v130, v24, v13
	v_add_u32_e32 v131, v24, v25
	v_lshlrev_b32_e32 v66, 1, v0
	v_writelane_b32 v254, s69, 63
	s_branch .LBB0_83
